# attention past-tile softmax: the 8 bias-table ds_read2_b32 per query group issued together with counted lgkmcnt waits; on top of v44
# speedup vs baseline: 1.0015x; 1.0007x over previous
; #define LAS __attribute__((address_space(3)))
; __device__ __forceinline__ void attn_phase(LAS unsigned char* lds, const bf16_t* QKV, const float* kmean, const float* biasT, bf16_t* O, int G, int wg) {
;     ...
;                 } else {
;                     const LAS float* bp = BT + (tq0 - key0 - fq * 4 - 63);
; #pragma unroll
;                     for (int st = 0; st < 4; ++st)
; #pragma unroll
;                         for (int j = 0; j < 4; ++j) { const float s = sc[z][st][j] + bp[63 - st * 16 - j + 16 * z]; sc[z][st][j] = s; mx = fmaxf(mx, s); }
;                     mx = selok ? mx : -1e30f;
.Lprio_qk_end:
	v_or_b32_e32 v236, s62, v222
	v_sub_u32_e32 v203, v180, v236
	v_lshl_add_u32 v250, v203, 2, s88
	s_lshl_b32 s61, 1, s0
	s_mov_b64 s[44:45], -1
	s_and_b64 vcc, exec, s[50:51]
	v_add_u32_e32 v249, -4, v250
	v_add_u32_e32 v246, -12, v250
	v_add_u32_e32 v245, 0xffffffbc, v250
	v_add_u32_e32 v244, 0xffffffb4, v250
	v_add_u32_e32 v243, 0xffffff7c, v250
	v_add_u32_e32 v204, 0xffffff74, v250
	s_cbranch_vccz .LBB0_1359
	v_and_b32_e32 v172, s61, v230
	v_cmp_ne_u32_e64 s[0:1], 0, v172
	v_add_u32_e32 v172, 0xffffff3c, v250
	v_add_u32_e32 v173, 0xffffff34, v250
	ds_read2_b32 v[186:187], v249 offset1:1
	ds_read2_b32 v[188:189], v246 offset1:1
	ds_read2_b32 v[190:191], v245 offset1:1
	ds_read2_b32 v[192:193], v244 offset1:1
	ds_read2_b32 v[194:195], v243 offset1:1
	ds_read2_b32 v[196:197], v204 offset1:1
	ds_read2_b32 v[198:199], v172 offset1:1
	ds_read2_b32 v[200:201], v173 offset1:1
	s_mov_b64 s[44:45], 0
	s_waitcnt lgkmcnt(7)
	v_pk_add_f32 v[186:187], v[140:141], v[186:187] op_sel:[0,1] op_sel_hi:[1,0]
	s_waitcnt lgkmcnt(6)
	v_pk_add_f32 v[188:189], v[142:143], v[188:189] op_sel:[0,1] op_sel_hi:[1,0]
	v_max3_f32 v176, v186, s90, v187
	s_waitcnt lgkmcnt(5)
	v_pk_add_f32 v[190:191], v[136:137], v[190:191] op_sel:[0,1] op_sel_hi:[1,0]
	v_max3_f32 v176, v176, v188, v189
	s_waitcnt lgkmcnt(4)
	v_pk_add_f32 v[192:193], v[138:139], v[192:193] op_sel:[0,1] op_sel_hi:[1,0]
	v_max3_f32 v176, v176, v190, v191
	s_waitcnt lgkmcnt(3)
	v_pk_add_f32 v[194:195], v[132:133], v[194:195] op_sel:[0,1] op_sel_hi:[1,0]
	v_max3_f32 v176, v176, v192, v193
	s_waitcnt lgkmcnt(2)
	v_pk_add_f32 v[196:197], v[134:135], v[196:197] op_sel:[0,1] op_sel_hi:[1,0]
	v_max3_f32 v176, v176, v194, v195
	s_waitcnt lgkmcnt(1)
	v_pk_add_f32 v[198:199], v[128:129], v[198:199] op_sel:[0,1] op_sel_hi:[1,0]
	v_max3_f32 v176, v176, v196, v197
	s_waitcnt lgkmcnt(0)
	v_pk_add_f32 v[200:201], v[130:131], v[200:201] op_sel:[0,1] op_sel_hi:[1,0]
	v_max3_f32 v176, v176, v198, v199
	s_nop 0
	v_max3_f32 v172, v176, v200, v201
	v_cndmask_b32_e64 v205, v215, v172, s[0:1]

; #define LAS __attribute__((address_space(3)))
; __device__ __forceinline__ void attn_phase(LAS unsigned char* lds, const bf16_t* QKV, const float* kmean, const float* biasT, bf16_t* O, int G, int wg) {
;     ...
;                 } else {
;                     const LAS float* bp = BT + (tq0 - key0 - fq * 4 - 63);
; #pragma unroll
;                     for (int st = 0; st < 4; ++st)
; #pragma unroll
;                         for (int j = 0; j < 4; ++j) { const float s = sc[z][st][j] + bp[63 - st * 16 - j + 16 * z]; sc[z][st][j] = s; mx = fmaxf(mx, s); }
;                     mx = selok ? mx : -1e30f;
.LBB0_1363:
	s_andn2_b64 vcc, exec, s[50:51]
	s_mov_b64 s[50:51], -1
	s_cbranch_vccnz .LBB0_1365
	v_and_b32_e32 v130, s61, v231
	v_cmp_ne_u32_e64 s[44:45], 0, v130
	ds_read2_b32 v[130:131], v250 offset0:15 offset1:16
	ds_read2_b32 v[132:133], v250 offset0:13 offset1:14
	ds_read2_b32 v[134:135], v249 offset1:1
	ds_read2_b32 v[136:137], v246 offset1:1
	ds_read2_b32 v[140:141], v245 offset1:1
	ds_read2_b32 v[142:143], v244 offset1:1
	ds_read2_b32 v[202:203], v243 offset1:1
	ds_read2_b32 v[176:177], v204 offset1:1
	s_mov_b64 s[50:51], 0
	s_waitcnt lgkmcnt(7)
	v_pk_add_f32 v[130:131], v[124:125], v[130:131] op_sel:[0,1] op_sel_hi:[1,0]
	s_waitcnt lgkmcnt(6)
	v_pk_add_f32 v[132:133], v[126:127], v[132:133] op_sel:[0,1] op_sel_hi:[1,0]
	v_max3_f32 v178, v130, s90, v131
	s_waitcnt lgkmcnt(5)
	v_pk_add_f32 v[134:135], v[120:121], v[134:135] op_sel:[0,1] op_sel_hi:[1,0]
	v_max3_f32 v178, v178, v132, v133
	s_waitcnt lgkmcnt(4)
	v_pk_add_f32 v[136:137], v[122:123], v[136:137] op_sel:[0,1] op_sel_hi:[1,0]
	v_max3_f32 v178, v178, v134, v135
	s_waitcnt lgkmcnt(3)
	v_pk_add_f32 v[140:141], v[116:117], v[140:141] op_sel:[0,1] op_sel_hi:[1,0]
	v_max3_f32 v178, v178, v136, v137
	s_waitcnt lgkmcnt(2)
	v_pk_add_f32 v[142:143], v[118:119], v[142:143] op_sel:[0,1] op_sel_hi:[1,0]
	v_max3_f32 v178, v178, v140, v141
	s_waitcnt lgkmcnt(1)
	v_pk_add_f32 v[202:203], v[112:113], v[202:203] op_sel:[0,1] op_sel_hi:[1,0]
	v_max3_f32 v178, v178, v142, v143
	s_waitcnt lgkmcnt(0)
	v_pk_add_f32 v[204:205], v[114:115], v[176:177] op_sel:[0,1] op_sel_hi:[1,0]
	v_max3_f32 v178, v178, v202, v203
	s_nop 0
	v_max3_f32 v176, v178, v204, v205
	v_cndmask_b32_e64 v176, v215, v176, s[44:45]
